# single-counter group barrier fast path when group on one XCD (no leader, no top stage)
# baseline (speedup 1.0000x reference)
; #define LAS __attribute__((address_space(3)))
; __global__ void __launch_bounds__(NTHREADS, 2) fwd(Args a) {
;     extern __shared__ __attribute__((aligned(16))) unsigned char lds_raw[];
;     LAS unsigned char* lds = (LAS unsigned char*)lds_raw;
;     const int tid = threadIdx.x, lane = tid & 63, wave = __builtin_amdgcn_readfirstlane(tid >> 6);
;     const int lo = a.ph_lo, hi = a.ph_hi;
;     if (tid < 64) ((LAS unsigned*)(lds + MISC_OFF))[tid] = 0u;
;     __syncthreads();
;     const int G = gridDim.x, GS = G / NGRP, b = (int)blockIdx.x % NGRP, r = (int)blockIdx.x / NGRP;
;     const bool in_group = r < GS;
;     XcdBarrier gbar = xcd_barrier_post((unsigned*)a.ws + NGRP * XCD_BAR_WORDS, (volatile LAS unsigned*)(lds + MISC_OFF), (unsigned)G);
;     XcdBarrier bar = gbar;
;     if (in_group) bar = xcd_barrier_post((unsigned*)a.ws + b * XCD_BAR_WORDS, (volatile LAS unsigned*)(lds + MISC_OFF) + 2, (unsigned)GS);
_Z3fwd4Args:
	s_mov_b32 s100, 0
	s_load_dwordx2 s[34:35], s[0:1], 0x90
	s_load_dwordx4 s[4:7], s[0:1], 0x80
	v_and_b32_e32 v201, 0x3ff, v0
	s_mov_b32 s10, s2
	v_readfirstlane_b32 s2, v201
	v_cmp_gt_u32_e32 vcc, 64, v201
	s_waitcnt lgkmcnt(0)
	v_writelane_b32 v230, s4, 0
	s_nop 1
	v_writelane_b32 v230, s5, 1
	v_writelane_b32 v230, s6, 2
	v_writelane_b32 v230, s7, 3
	v_writelane_b32 v230, s2, 4
	s_and_saveexec_b64 s[2:3], vcc
	v_lshl_add_u32 v1, v201, 2, 0
	v_add_u32_e32 v1, 0x24000, v1
	v_mov_b32_e32 v2, 0
	ds_write_b32 v1, v2
	s_or_b64 exec, exec, s[2:3]
	s_waitcnt lgkmcnt(0)
	s_barrier
	s_load_dwordx2 s[52:53], s[0:1], 0x98
	s_load_dword s28, s[0:1], 0xa0
	s_add_u32 s60, s0, 0xa0
	s_addc_u32 s61, s1, 0
	s_add_u32 s58, s34, 0x1b000
	s_getreg_b32 s2, hwreg(HW_REG_XCC_ID, 0, 4)
	s_addc_u32 s59, s35, 0
	s_and_b32 s7, s2, 15
	v_cmp_eq_u32_e64 s[8:9], 0, v201
	s_and_saveexec_b64 s[2:3], s[8:9]
	s_cbranch_execz .LBB0_5
	s_mov_b64 s[4:5], exec
	v_mbcnt_lo_u32_b32 v1, s4, 0
	v_mbcnt_hi_u32_b32 v1, s5, v1
	v_cmp_eq_u32_e32 vcc, 0, v1
	s_and_b64 s[12:13], exec, vcc
	s_mov_b64 exec, s[12:13]
	s_cbranch_execz .LBB0_5
	s_lshl_b32 s6, s7, 8
	s_bcnt1_i32_b64 s4, s[4:5]
	v_mov_b32_e32 v1, s6
	v_mov_b32_e32 v2, s4
	global_atomic_add v1, v2, s[58:59] offset:1024

; __device__ __forceinline__ unsigned xb_ld(unsigned* p)              { return __hip_atomic_load(p, __ATOMIC_RELAXED, __HIP_MEMORY_SCOPE_AGENT); }
; __device__ __forceinline__ unsigned xb_add(unsigned* p, unsigned v) { return __hip_atomic_fetch_add(p, v, __ATOMIC_RELAXED, __HIP_MEMORY_SCOPE_AGENT); }
; #define XB_SPIN(cond, bar) do { unsigned _sp = 0; while (cond) { __builtin_amdgcn_s_sleep(1); \
;     if ((++_sp & 255u) == 0u) { if (xb_ld(&(bar)[XB_TMO])) break; if (_sp > XB_SPIN_CAP) { atomicAdd(&(bar)[XB_TMO], 1u); break; } } } } while (0)
; __device__ __forceinline__ void xcd_barrier(const XcdBarrier& b) {
;     ...
;     if (threadIdx.x == 0) {
;         unsigned* bar = b.bar;
;         __builtin_amdgcn_s_waitcnt(0);
;         unsigned nloc = b.st[0], nx = b.st[1];
;         if (nloc == 0u) { xcd_barrier_complete(bar, b.x, b.gsz, nloc, nx); b.st[0] = nloc; b.st[1] = nx; }
;         const unsigned old = xb_add(&bar[XB_XSUB(b.x)], 1u);
;         const unsigned gen = old / nloc;
;         if (old + 1u == (gen + 1u) * nloc) {
;             __builtin_amdgcn_fence(__ATOMIC_RELEASE, "agent");
;             asm volatile("s_waitcnt vmcnt(0)" ::: "memory");
;             const unsigned og = xb_add(&bar[XB_TOP], 1u);
;             const unsigned tg = og / nx;
;             if (og + 1u == (tg + 1u) * nx) xb_add(&bar[XB_TOPGEN], 1u);
;             else XB_SPIN(xb_ld(&bar[XB_TOPGEN]) == tg, bar);
;             __builtin_amdgcn_fence(__ATOMIC_ACQUIRE, "agent");
;             xb_add(&bar[XB_XGEN(b.x)], 1u);
;             asm volatile("s_waitcnt vmcnt(0)" ::: "memory");
;         } else {
;             XB_SPIN(xb_ld(&bar[XB_XGEN(b.x)]) == gen, bar);
;             __builtin_amdgcn_fence(__ATOMIC_ACQUIRE, "agent");
;             asm volatile("s_waitcnt vmcnt(0)" ::: "memory");
;         }
.LBB0_199:
	s_waitcnt lgkmcnt(0)
	v_cmp_ne_u32_e32 vcc, 1, v0
	s_cbranch_vccnz .Lxslow_1
	s_lshl_b32 s4, s33, 8
	s_add_u32 s4, s54, s4
	s_addc_u32 s5, s55, 0
	s_add_i32 s100, s100, 1
	v_mov_b32_e32 v1, 0x1000
	v_mov_b32_e32 v3, 1
	global_atomic_add v1, v3, s[4:5] offset:1024
	v_mul_lo_u32 v2, v2, s100
	s_mov_b32 s101, 0
.Lxspin_1:
	global_load_dword v0, v1, s[4:5] offset:1024 sc1
	s_waitcnt vmcnt(0)
	v_sub_u32_e32 v0, v0, v2
	v_cmp_gt_i32_e32 vcc, 0, v0
	s_cbranch_vccz .Lxdone_1
	s_add_i32 s101, s101, 1
	s_cmp_gt_u32 s101, 0x8000
	s_cbranch_scc1 .Lxdone_1
	s_sleep 1
	s_branch .Lxspin_1
.Lxdone_1:
	buffer_inv sc1
	s_waitcnt vmcnt(0)
	s_branch .LBB0_228

; __device__ __forceinline__ unsigned xb_ld(unsigned* p)              { return __hip_atomic_load(p, __ATOMIC_RELAXED, __HIP_MEMORY_SCOPE_AGENT); }
; __device__ __forceinline__ unsigned xb_add(unsigned* p, unsigned v) { return __hip_atomic_fetch_add(p, v, __ATOMIC_RELAXED, __HIP_MEMORY_SCOPE_AGENT); }
; #define XB_SPIN(cond, bar) do { unsigned _sp = 0; while (cond) { __builtin_amdgcn_s_sleep(1); \
;     if ((++_sp & 255u) == 0u) { if (xb_ld(&(bar)[XB_TMO])) break; if (_sp > XB_SPIN_CAP) { atomicAdd(&(bar)[XB_TMO], 1u); break; } } } } while (0)
; __device__ __forceinline__ void xcd_barrier(const XcdBarrier& b) {
;     ...
;     if (threadIdx.x == 0) {
;         unsigned* bar = b.bar;
;         __builtin_amdgcn_s_waitcnt(0);
;         unsigned nloc = b.st[0], nx = b.st[1];
;         if (nloc == 0u) { xcd_barrier_complete(bar, b.x, b.gsz, nloc, nx); b.st[0] = nloc; b.st[1] = nx; }
;         const unsigned old = xb_add(&bar[XB_XSUB(b.x)], 1u);
;         const unsigned gen = old / nloc;
;         if (old + 1u == (gen + 1u) * nloc) {
;             __builtin_amdgcn_fence(__ATOMIC_RELEASE, "agent");
;             asm volatile("s_waitcnt vmcnt(0)" ::: "memory");
;             const unsigned og = xb_add(&bar[XB_TOP], 1u);
;             const unsigned tg = og / nx;
;             if (og + 1u == (tg + 1u) * nx) xb_add(&bar[XB_TOPGEN], 1u);
;             else XB_SPIN(xb_ld(&bar[XB_TOPGEN]) == tg, bar);
;             __builtin_amdgcn_fence(__ATOMIC_ACQUIRE, "agent");
;             xb_add(&bar[XB_XGEN(b.x)], 1u);
;             asm volatile("s_waitcnt vmcnt(0)" ::: "memory");
;         } else {
;             XB_SPIN(xb_ld(&bar[XB_XGEN(b.x)]) == gen, bar);
;             __builtin_amdgcn_fence(__ATOMIC_ACQUIRE, "agent");
;             asm volatile("s_waitcnt vmcnt(0)" ::: "memory");
;         }
.LBB0_490:
	s_waitcnt lgkmcnt(0)
	v_cmp_ne_u32_e32 vcc, 1, v0
	s_cbranch_vccnz .Lxslow_5
	s_lshl_b32 s2, s33, 8
	s_add_u32 s4, s54, s2
	s_addc_u32 s5, s55, 0
	s_add_i32 s100, s100, 1
	v_mov_b32_e32 v1, 0x1000
	v_mov_b32_e32 v3, 1
	global_atomic_add v1, v3, s[4:5] offset:1024
	v_mul_lo_u32 v2, v2, s100
	s_mov_b32 s101, 0

; __device__ __forceinline__ unsigned xb_ld(unsigned* p)              { return __hip_atomic_load(p, __ATOMIC_RELAXED, __HIP_MEMORY_SCOPE_AGENT); }
; __device__ __forceinline__ unsigned xb_add(unsigned* p, unsigned v) { return __hip_atomic_fetch_add(p, v, __ATOMIC_RELAXED, __HIP_MEMORY_SCOPE_AGENT); }
; #define XB_SPIN(cond, bar) do { unsigned _sp = 0; while (cond) { __builtin_amdgcn_s_sleep(1); \
;     if ((++_sp & 255u) == 0u) { if (xb_ld(&(bar)[XB_TMO])) break; if (_sp > XB_SPIN_CAP) { atomicAdd(&(bar)[XB_TMO], 1u); break; } } } } while (0)
; __device__ __forceinline__ void xcd_barrier(const XcdBarrier& b) {
;     ...
;     if (threadIdx.x == 0) {
;         unsigned* bar = b.bar;
;         __builtin_amdgcn_s_waitcnt(0);
;         unsigned nloc = b.st[0], nx = b.st[1];
;         if (nloc == 0u) { xcd_barrier_complete(bar, b.x, b.gsz, nloc, nx); b.st[0] = nloc; b.st[1] = nx; }
;         const unsigned old = xb_add(&bar[XB_XSUB(b.x)], 1u);
;         const unsigned gen = old / nloc;
;         if (old + 1u == (gen + 1u) * nloc) {
;             __builtin_amdgcn_fence(__ATOMIC_RELEASE, "agent");
;             asm volatile("s_waitcnt vmcnt(0)" ::: "memory");
;             const unsigned og = xb_add(&bar[XB_TOP], 1u);
;             const unsigned tg = og / nx;
;             if (og + 1u == (tg + 1u) * nx) xb_add(&bar[XB_TOPGEN], 1u);
;             else XB_SPIN(xb_ld(&bar[XB_TOPGEN]) == tg, bar);
;             __builtin_amdgcn_fence(__ATOMIC_ACQUIRE, "agent");
;             xb_add(&bar[XB_XGEN(b.x)], 1u);
;             asm volatile("s_waitcnt vmcnt(0)" ::: "memory");
;         } else {
;             XB_SPIN(xb_ld(&bar[XB_XGEN(b.x)]) == gen, bar);
;             __builtin_amdgcn_fence(__ATOMIC_ACQUIRE, "agent");
;             asm volatile("s_waitcnt vmcnt(0)" ::: "memory");
;         }
.LBB0_540:
	s_waitcnt lgkmcnt(0)
	v_cmp_ne_u32_e32 vcc, 1, v0
	s_cbranch_vccnz .Lxslow_6
	s_lshl_b32 s2, s33, 8
	s_add_u32 s6, s54, s2
	s_addc_u32 s7, s55, 0
	s_add_i32 s100, s100, 1
	v_mov_b32_e32 v1, 0x1000
	v_mov_b32_e32 v3, 1
	global_atomic_add v1, v3, s[6:7] offset:1024
	v_mul_lo_u32 v2, v2, s100
	s_mov_b32 s101, 0
.Lxspin_6:
	global_load_dword v0, v1, s[6:7] offset:1024 sc1
	s_waitcnt vmcnt(0)
	v_sub_u32_e32 v0, v0, v2
	v_cmp_gt_i32_e32 vcc, 0, v0
	s_cbranch_vccz .Lxdone_6
	s_add_i32 s101, s101, 1
	s_cmp_gt_u32 s101, 0x8000
	s_cbranch_scc1 .Lxdone_6
	s_sleep 1
	s_branch .Lxspin_6

; __global__ void __launch_bounds__(NTHREADS, 2) fwd(Args a) {
	.amdhsa_kernel _Z3fwd4Args
		.amdhsa_group_segment_fixed_size 0
		.amdhsa_private_segment_fixed_size 0
		.amdhsa_kernarg_size 416
		.amdhsa_user_sgpr_count 2
		.amdhsa_user_sgpr_dispatch_ptr 0
		.amdhsa_user_sgpr_queue_ptr 0
		.amdhsa_user_sgpr_kernarg_segment_ptr 1
		.amdhsa_user_sgpr_dispatch_id 0
		.amdhsa_user_sgpr_kernarg_preload_length 0
		.amdhsa_user_sgpr_kernarg_preload_offset 0
		.amdhsa_user_sgpr_private_segment_size 0
		.amdhsa_uses_dynamic_stack 0
		.amdhsa_enable_private_segment 0
		.amdhsa_system_sgpr_workgroup_id_x 1
		.amdhsa_system_sgpr_workgroup_id_y 0
		.amdhsa_system_sgpr_workgroup_id_z 0
		.amdhsa_system_sgpr_workgroup_info 0
		.amdhsa_system_vgpr_workitem_id 2
		.amdhsa_next_free_vgpr 231
		.amdhsa_next_free_sgpr 102
		.amdhsa_accum_offset 232
		.amdhsa_reserve_vcc 1
		.amdhsa_float_round_mode_32 0
		.amdhsa_float_round_mode_16_64 0
		.amdhsa_float_denorm_mode_32 3
		.amdhsa_float_denorm_mode_16_64 3
		.amdhsa_dx10_clamp 1
		.amdhsa_ieee_mode 1
		.amdhsa_fp16_overflow 0
		.amdhsa_tg_split 0
		.amdhsa_exception_fp_ieee_invalid_op 0
		.amdhsa_exception_fp_denorm_src 0
		.amdhsa_exception_fp_ieee_div_zero 0
		.amdhsa_exception_fp_ieee_overflow 0
		.amdhsa_exception_fp_ieee_underflow 0
		.amdhsa_exception_fp_ieee_inexact 0
		.amdhsa_exception_int_div_zero 0
	.end_amdhsa_kernel

; __global__ void __launch_bounds__(NTHREADS, 2) fwd(Args a) {
amdhsa.kernels:
  - .agpr_count:     0
    .args:
      - .offset:         0
        .size:           160
        .value_kind:     by_value
      - .offset:         160
        .size:           4
        .value_kind:     hidden_block_count_x
      - .offset:         164
        .size:           4
        .value_kind:     hidden_block_count_y
      - .offset:         168
        .size:           4
        .value_kind:     hidden_block_count_z
      - .offset:         172
        .size:           2
        .value_kind:     hidden_group_size_x
      - .offset:         174
        .size:           2
        .value_kind:     hidden_group_size_y
      - .offset:         176
        .size:           2
        .value_kind:     hidden_group_size_z
      - .offset:         178
        .size:           2
        .value_kind:     hidden_remainder_x
      - .offset:         180
        .size:           2
        .value_kind:     hidden_remainder_y
      - .offset:         182
        .size:           2
        .value_kind:     hidden_remainder_z
      - .offset:         200
        .size:           8
        .value_kind:     hidden_global_offset_x
      - .offset:         208
        .size:           8
        .value_kind:     hidden_global_offset_y
      - .offset:         216
        .size:           8
        .value_kind:     hidden_global_offset_z
      - .offset:         224
        .size:           2
        .value_kind:     hidden_grid_dims
      - .offset:         248
        .size:           8
        .value_kind:     hidden_multigrid_sync_arg
      - .offset:         280
        .size:           4
        .value_kind:     hidden_dynamic_lds_size
    .group_segment_fixed_size: 0
    .kernarg_segment_align: 8
    .kernarg_segment_size: 416
    .language:       OpenCL C
    .language_version:
      - 2
      - 0
    .max_flat_workgroup_size: 512
    .name:           _Z3fwd4Args
    .private_segment_fixed_size: 0
    .sgpr_count:     108
    .sgpr_spill_count: 16
    .symbol:         _Z3fwd4Args.kd
    .uniform_work_group_size: 1
    .uses_dynamic_stack: false
    .vgpr_count:     231
    .vgpr_spill_count: 0
    .wavefront_size: 64
